# speed-ranked GU tail: the 96-tile last round of the GU GEMM goes to the three fastest bid%8 groups (ranked once at the barrier after step-0 GU), slow XCD does 12 units (on keep_v7)
# speedup vs baseline: 1.0047x; 1.0047x over previous
.LBB0_840:
	s_add_u32 s6, s6, 0xac00000
	s_addc_u32 s7, s7, 0
	v_and_b32_e32 v17, 15, v16
	v_lshrrev_b32_e32 v18, 1, v16
	s_lshl_b32 s2, s2, 5
	v_and_b32_e32 v18, 24, v18
	v_lshlrev_b32_e32 v19, 6, v17
	v_lshlrev_b32_e32 v16, 2, v16
	s_and_b32 s22, s2, 0x60
	s_add_i32 m0, s46, 0x18000
	v_lshl_add_u64 v[8:9], v[8:9], 0, s[70:71]
	v_lshl_or_b32 v19, v18, 1, v19
	v_and_b32_e32 v16, 32, v16
	v_lshl_or_b32 v144, s3, 6, v17
	s_lshl_b32 s3, s3, 13
	s_lshl_b32 s2, s22, 7
	s_waitcnt vmcnt(2)
	s_barrier
	global_load_lds_dwordx4 v[8:9], off
	v_lshl_add_u64 v[6:7], v[6:7], 0, s[70:71]
	s_add_i32 m0, s46, 0x1a000
	s_add_i32 s50, s46, 0x8000
	s_add_i32 s51, s46, 0xa000
	v_bitop3_b32 v145, s2, v19, v16 bitop3:0xf6
	global_load_lds_dwordx4 v[6:7], off
	v_lshl_add_u64 v[2:3], v[2:3], 0, s[70:71]
	s_mov_b32 m0, s50
	s_add_u32 s2, s38, 0x40080
	v_bitop3_b32 v17, v19, s3, v16 bitop3:0xde
	global_load_lds_dwordx4 v[2:3], off
	v_lshl_add_u64 v[2:3], v[4:5], 0, s[70:71]
	s_mov_b32 m0, s51
	s_addc_u32 s3, s39, 0
	global_load_lds_dwordx4 v[2:3], off
	s_add_i32 m0, s46, 0x1c000
	v_lshl_add_u64 v[2:3], s[2:3], 0, v[0:1]
	global_load_lds_dwordx4 v[2:3], off
	v_lshl_add_u64 v[2:3], s[2:3], 0, v[134:135]
	s_add_i32 m0, s46, 0x1e000
	s_cmpk_lt_u32 s9, 0x100
	global_load_lds_dwordx4 v[2:3], off
	v_lshlrev_b32_e32 v2, 14, v10
	v_and_b32_e32 v2, 0xffff8000, v2
	v_lshl_add_u32 v2, v11, 11, v2
	v_and_b32_e32 v3, 1, v10
	v_lshl_or_b32 v2, v3, 6, v2
	v_lshl_add_u32 v136, v12, 1, v2
	v_lshlrev_b32_e32 v2, 14, v13
	v_and_b32_e32 v2, 0xffff8000, v2
	s_waitcnt vmcnt(6)
	v_lshl_add_u32 v2, v14, 11, v2
	v_and_b32_e32 v3, 1, v13
	v_lshl_or_b32 v2, v3, 6, v2
	s_cselect_b64 s[14:15], -1, 0
	v_or_b32_e32 v146, s22, v18
	v_mov_b32_e32 v137, v1
	v_lshl_add_u32 v138, v15, 1, v2
	v_mov_b32_e32 v139, v1
	s_mov_b32 s52, 0
	v_add_u32_e32 v147, 0, v17
	s_barrier
	s_mov_b32 s100, 0x10000
	s_cmp_eq_u32 s65, 0
	s_cbranch_scc1 .Lslot_done
	s_cmpk_lg_u32 s33, 0x100
	s_cbranch_scc1 .Lslot_done
	s_load_dwordx2 s[98:99], s[0:1], 0x128
	s_and_b32 s101, s8, 7
	s_lshl_b32 s101, s101, 8
	s_waitcnt lgkmcnt(0)
	s_add_u32 s98, s98, s101
	s_addc_u32 s99, s99, 0
	s_add_u32 s98, s98, 0x302400
	s_addc_u32 s99, s99, 0
	global_load_dword v2, v1, s[98:99] sc1
	s_waitcnt vmcnt(0)
	v_readfirstlane_b32 s101, v2
	s_nop 3
	s_cmp_lt_u32 s101, 3
	s_cbranch_scc0 .Lslot_done
	s_lshl_b32 s101, s101, 5
	s_lshr_b32 s100, s8, 3
	s_add_i32 s100, s100, s101
.Lslot_done:
	s_branch .LBB0_843

.LBB0_843:
	s_add_i32 s52, s52, 1
	s_mul_i32 s2, s52, s34
	s_mul_hi_u32 s3, s52, s33
	s_add_i32 s3, s3, s2
	s_mul_i32 s2, s52, s33
	s_add_u32 s26, s2, s8
	s_addc_u32 s27, s3, s55
	s_cmp_lg_u32 s52, 12
	s_cbranch_scc1 .Ltail_done
	s_cmp_eq_u32 s65, 0
	s_cbranch_scc1 .Ltail_done
	s_cmpk_lg_u32 s33, 0x100
	s_cbranch_scc1 .Ltail_done
	s_add_i32 s26, s100, 0xc00
	s_mov_b32 s27, 0
.Ltail_done:
	v_mov_b64_e32 v[2:3], s[20:21]
	v_cmp_ge_i64_e32 vcc, s[26:27], v[2:3]
	v_cmp_lt_i64_e64 s[2:3], s[26:27], v[2:3]
	s_cbranch_vccnz .LBB0_845
	s_ashr_i32 s9, s26, 31
	s_lshr_b32 s9, s9, 29
	s_add_i32 s9, s26, s9
	s_ashr_i32 s22, s9, 3
	s_and_b32 s9, s9, -8
	s_sub_i32 s9, s26, s9
	s_cmp_lt_i32 s9, 0
	s_cselect_b32 s23, s44, s43
	s_mul_i32 s9, s23, s9
	s_add_i32 s9, s9, s22
	s_mul_hi_i32 s22, s9, 0x2e8ba2e9
	s_lshr_b32 s23, s22, 31
	s_ashr_i32 s22, s22, 5
	s_add_i32 s22, s22, s23
	s_lshl_b32 s23, s22, 3
	s_sub_i32 s24, s40, s23
	s_min_i32 s24, s24, 8
	s_abs_i32 s25, s24
	v_cvt_f32_u32_e32 v2, s25
	s_sub_i32 s27, 0, s25
	s_mulk_i32 s22, 0xb0
	s_sub_i32 s9, s9, s22
	v_rcp_iflag_f32_e32 v2, v2
	s_abs_i32 s22, s9
	s_xor_b32 s26, s9, s24
	s_ashr_i32 s26, s26, 31
	v_mul_f32_e32 v2, 0x4f7ffffe, v2
	v_cvt_u32_f32_e32 v2, v2
	s_nop 0
	v_readfirstlane_b32 s28, v2
	s_mul_i32 s27, s27, s28
	s_mul_hi_u32 s27, s28, s27
	s_add_i32 s28, s28, s27
	s_mul_hi_u32 s27, s22, s28
	s_mul_i32 s28, s27, s25
	s_sub_i32 s22, s22, s28
	s_add_i32 s29, s27, 1
	s_sub_i32 s28, s22, s25
	s_cmp_ge_u32 s22, s25
	s_cselect_b32 s27, s29, s27
	s_cselect_b32 s22, s28, s22
	s_add_i32 s28, s27, 1
	s_cmp_ge_u32 s22, s25
	s_cselect_b32 s22, s28, s27
	s_xor_b32 s22, s22, s26
	s_sub_i32 s22, s22, s26
	s_mul_i32 s24, s22, s24
	s_sub_i32 s9, s9, s24
	s_add_i32 s24, s9, s23

.LBB0_869:
	s_cmp_lg_u32 s65, 0
	s_cbranch_scc1 .Lrk_done
	s_cmp_gt_u32 s8, 7
	s_cbranch_scc1 .Lrk_done
	s_add_u32 s98, s4, 0x302c00
	s_addc_u32 s99, s5, 0
	global_atomic_add v4, v1, v245, s[98:99] sc0
	s_lshl_b32 s100, s8, 8
	s_add_u32 s98, s4, s100
	s_addc_u32 s99, s5, 0
	s_add_u32 s98, s98, 0x302400
	s_addc_u32 s99, s99, 0
	s_waitcnt vmcnt(0)
	global_store_dword v1, v4, s[98:99]
	s_waitcnt vmcnt(0)
